# SB loops: 24 more dead VALU instructions removed (compare/xor/add/and of the old bpermute lane address in the three other tile bodies); placement of later loops preserved
# baseline (speedup 1.0000x reference)
; DEV f32x16 mfma32(bf16x8 a, bf16x8 b, f32x16 c) { return __builtin_amdgcn_mfma_f32_32x32x16_bf16(a, b, c, 0, 0, 0); }
; template <bool DIAG>
; DEV void sb_tile(const char* lk, const char* lv, const int ko0, const int vo0, const bf16x8 (&qf)[8], f32x16 (&O)[4], float& accp,
;                  const int l31, const int hh) {
;   f32x16 z;
;   for (int g = 0; g < 16; ++g) z[g] = 0.f;
;   {
;     bf16x8 kf[8];
; #pragma unroll
;     for (int s = 0; s < 8; ++s) kf[s] = *(const bf16x8*)(lk + (ko0 ^ (32 * s)));
;     __builtin_amdgcn_sched_barrier(0);
; #pragma unroll
;     for (int s = 0; s < 8; ++s) z = mfma32(kf[s], qf[s], z);
;   }
;   bf16x8 vf[4][2];
; #pragma unroll
;   for (int d = 0; d < 4; ++d) { vf[d][0] = *(const bf16x8*)(lv + d * 4096 + vo0); vf[d][1] = *(const bf16x8*)(lv + d * 4096 + (vo0 ^ 32)); }
;   __builtin_amdgcn_sched_barrier(0);
;   float be[16], om[16];
; #pragma unroll
;   for (int g = 0; g < 16; ++g) {
;     const float e = __builtin_amdgcn_exp2f(fminf(-z[g], 120.f));
;     be[g] = __builtin_amdgcn_rcpf(1.f + e);
;     om[g] = e * be[g];
;     if (DIAG) { const int kl = (g & 3) + 8 * (g >> 2) + 4 * hh; if (kl >= l31) { be[g] = 0.f; om[g] = 1.f; } }
;   }
;   float gp[4], pp[4], tot[4];
; #pragma unroll
;   for (int q = 0; q < 4; ++q) { gp[q] = (om[4 * q] * om[4 * q + 1]) * (om[4 * q + 2] * om[4 * q + 3]); pp[q] = __shfl_xor(gp[q], 32); tot[q] = gp[q] * pp[q]; }
;   float suf[4];
;   suf[3] = accp; suf[2] = suf[3] * tot[3]; suf[1] = suf[2] * tot[2]; suf[0] = suf[1] * tot[1];
.LBB0_563:
	s_andn2_b64 vcc, exec, s[66:67]
	s_cbranch_vccnz .LBB0_565
	ds_read_b128 v[64:67], v240 offset:8192
	ds_read_b128 v[80:83], v241 offset:8192
	ds_read_b128 v[84:87], v242 offset:8192
	ds_read_b128 v[88:91], v243 offset:8192
	ds_read_b128 v[92:95], v244 offset:8192
	ds_read_b128 v[96:99], v245 offset:8192
	ds_read_b128 v[100:103], v246 offset:8192
	ds_read_b128 v[112:115], v247 offset:8192
	s_waitcnt lgkmcnt(0)
	v_mfma_f32_32x32x16_bf16 v[64:79], v[64:67], v[128:131], 0
	v_mfma_f32_32x32x16_bf16 v[64:79], v[80:83], v[132:135], v[64:79]
	v_mfma_f32_32x32x16_bf16 v[64:79], v[84:87], v[136:139], v[64:79]
	v_mfma_f32_32x32x16_bf16 v[64:79], v[88:91], v[140:143], v[64:79]
	v_mfma_f32_32x32x16_bf16 v[64:79], v[92:95], v[144:147], v[64:79]
	v_mfma_f32_32x32x16_bf16 v[64:79], v[96:99], v[148:151], v[64:79]
	v_mfma_f32_32x32x16_bf16 v[64:79], v[100:103], v[152:155], v[64:79]
	ds_read_b128 v[108:111], v250
	ds_read_b128 v[96:99], v250 offset:4096
	ds_read_b128 v[104:107], v251
	ds_read_b128 v[100:103], v251 offset:4096
	ds_read_b128 v[88:91], v250 offset:8192
	ds_read_b128 v[84:87], v250 offset:12288
	ds_read_b128 v[92:95], v251 offset:8192
	ds_read_b128 v[80:83], v251 offset:12288
	v_mfma_f32_32x32x16_bf16 v[64:79], v[112:115], v[156:159], v[64:79]
	s_nop 11
	v_min_f32_e64 v64, -v64, s32
	v_exp_f32_e32 v64, v64
	v_min_f32_e64 v65, -v65, s32
	v_exp_f32_e32 v65, v65
	v_add_f32_e32 v112, 1.0, v64
	v_rcp_f32_e32 v120, v112
	v_add_f32_e32 v112, 1.0, v65
	v_min_f32_e64 v66, -v66, s32
	v_rcp_f32_e32 v121, v112
	v_exp_f32_e32 v112, v66
	v_min_f32_e64 v66, -v67, s32
	v_exp_f32_e32 v67, v66
	v_add_f32_e32 v66, 1.0, v112
	v_rcp_f32_e32 v122, v66
	v_mul_f32_e32 v65, v65, v121
	v_add_f32_e32 v66, 1.0, v67
	v_rcp_f32_e32 v123, v66
	v_cndmask_b32_e64 v66, 1.0, v65, s[14:15]
	v_mul_f32_e32 v65, v112, v122
	v_cndmask_b32_e64 v112, 1.0, v65, s[16:17]
	v_mul_f32_e32 v65, v67, v123
	v_min_f32_e64 v67, -v68, s32
	v_exp_f32_e32 v67, v67
	v_min_f32_e64 v68, -v69, s32
	v_exp_f32_e32 v69, v68
	v_cndmask_b32_e64 v68, 1.0, v65, s[18:19]
	v_add_f32_e32 v65, 1.0, v67
	v_rcp_f32_e32 v124, v65
	v_add_f32_e32 v65, 1.0, v69
	v_rcp_f32_e32 v125, v65
	v_min_f32_e64 v65, -v70, s32
	v_exp_f32_e32 v65, v65
	v_mul_f32_e32 v67, v67, v124
	v_cndmask_b32_e64 v70, 1.0, v67, s[20:21]
	v_mul_f32_e32 v67, v69, v125
	v_add_f32_e32 v69, 1.0, v65
	v_rcp_f32_e32 v126, v69
	v_min_f32_e64 v69, -v71, s32
	v_exp_f32_e32 v69, v69
	v_mul_f32_e32 v65, v65, v126
	v_cndmask_b32_e64 v115, 1.0, v65, s[24:25]
	v_cndmask_b32_e64 v114, 1.0, v67, s[22:23]
	v_add_f32_e32 v65, 1.0, v69
	v_rcp_f32_e32 v127, v65
	v_min_f32_e64 v65, -v72, s32
	v_exp_f32_e32 v65, v65
	v_min_f32_e64 v67, -v73, s32
	v_exp_f32_e32 v67, v67
	v_mul_f32_e32 v69, v69, v127
	v_add_f32_e32 v71, 1.0, v65
	v_rcp_f32_e32 v160, v71
	v_add_f32_e32 v71, 1.0, v67
	v_rcp_f32_e32 v161, v71
	v_cndmask_b32_e64 v71, 1.0, v69, s[26:27]
	v_mul_f32_e32 v65, v65, v160
	v_cndmask_b32_e64 v72, 1.0, v65, s[28:29]
	v_mul_f32_e32 v65, v67, v161
	v_min_f32_e64 v67, -v74, s32
	v_exp_f32_e32 v67, v67
	v_min_f32_e64 v69, -v75, s32
	v_exp_f32_e32 v69, v69
	v_cndmask_b32_e64 v74, 1.0, v65, s[30:31]
	v_add_f32_e32 v65, 1.0, v67
	v_rcp_f32_e32 v162, v65
	v_add_f32_e32 v65, 1.0, v69
	v_rcp_f32_e32 v163, v65
	v_min_f32_e64 v65, -v76, s32
	v_exp_f32_e32 v65, v65
	v_mul_f32_e32 v67, v67, v162
	v_cndmask_b32_e64 v75, 1.0, v67, s[34:35]
	v_mul_f32_e32 v67, v69, v163
	v_add_f32_e32 v69, 1.0, v65
	v_rcp_f32_e32 v164, v69
	v_min_f32_e64 v69, -v77, s32
	v_exp_f32_e32 v69, v69
	v_mul_f32_e32 v65, v65, v164
	v_cndmask_b32_e64 v76, 1.0, v65, s[38:39]
	v_cndmask_b32_e64 v73, 1.0, v67, s[36:37]
	v_add_f32_e32 v65, 1.0, v69
	v_rcp_f32_e32 v165, v65
	v_min_f32_e64 v65, -v78, s32
	v_exp_f32_e32 v65, v65
	v_min_f32_e64 v67, -v79, s32
	v_exp_f32_e32 v67, v67
	v_mul_f32_e32 v69, v69, v165
	v_add_f32_e32 v77, 1.0, v65
	v_rcp_f32_e32 v166, v77
	v_add_f32_e32 v77, 1.0, v67
	v_rcp_f32_e32 v167, v77
	v_cndmask_b32_e64 v78, 1.0, v69, s[40:41]
	v_mul_f32_e32 v65, v65, v166
	v_cndmask_b32_e64 v79, 1.0, v65, s[42:43]
	v_mul_f32_e32 v65, v67, v167
	v_cndmask_b32_e64 v77, 1.0, v65, s[44:45]
	v_pk_mul_f32 v[116:117], v[74:75], v[72:73]
	v_mul_f32_e32 v64, v64, v120
	v_mul_f32_e32 v65, v116, v117
	v_pk_mul_f32 v[116:117], v[78:79], v[76:77]
	v_mov_b32_e32 v72, v65
	s_nop 1
	v_permlane32_swap_b32_e32 v65, v72
	v_mul_f32_e32 v69, v116, v117
	v_mov_b32_e32 v76, v69
	s_nop 1
	v_permlane32_swap_b32_e32 v69, v76
	v_pk_mul_f32 v[116:117], v[114:115], v[70:71]
	v_cndmask_b32_e64 v64, 1.0, v64, s[12:13]
	v_pk_mul_f32 v[116:117], v[116:117], v[116:117] op_sel:[0,1] op_sel_hi:[1,0]
	v_mov_b32_e32 v67, v116
	s_nop 1
	v_permlane32_swap_b32_e32 v116, v67
	s_waitcnt lgkmcnt(0)
	v_mul_f32_e32 v113, v65, v72
	v_mul_f32_e32 v65, v69, v76
	v_mul_f32_e32 v69, v197, v65
	v_mov_b32_e32 v65, v116
	v_pk_mul_f32 v[64:65], v[64:65], v[66:67]
	v_pk_mul_f32 v[116:117], v[112:113], v[68:69]
	v_cndmask_b32_e64 v113, 1.0, v67, s[10:11]
	v_pk_mul_f32 v[118:119], v[64:65], v[116:117]
	v_mov_b32_e32 v116, v118
	s_nop 1
	v_permlane32_swap_b32_e32 v118, v116
	v_cndmask_b32_e64 v67, 1.0, v72, s[10:11]
	v_cndmask_b32_e64 v65, 0, v121, s[14:15]
	v_cndmask_b32_e64 v121, 0, v123, s[18:19]
	v_cndmask_b32_e64 v123, 0, v125, s[22:23]
	s_waitcnt lgkmcnt(0)
; DEV f32x16 mfma32(bf16x8 a, bf16x8 b, f32x16 c) { return __builtin_amdgcn_mfma_f32_32x32x16_bf16(a, b, c, 0, 0, 0); }
; template <bool DIAG>
; DEV void sb_tile(const char* lk, const char* lv, const int ko0, const int vo0, const bf16x8 (&qf)[8], f32x16 (&O)[4], float& accp,
;                  const int l31, const int hh) {
;     ...
;   f32x16 w;
; #pragma unroll
;   for (int q = 0; q < 4; ++q) {
;     float a = suf[q] * (hh == 0 ? pp[q] : 1.f);
;     w[4 * q + 3] = be[4 * q + 3] * a; a *= om[4 * q + 3];
;     w[4 * q + 2] = be[4 * q + 2] * a; a *= om[4 * q + 2];
;     w[4 * q + 1] = be[4 * q + 1] * a; a *= om[4 * q + 1];
;     w[4 * q + 0] = be[4 * q + 0] * a;
;   }
;   const bf16x8 w0 = cvt8<0>(w), w1 = cvt8<1>(w);
; #pragma unroll
;   for (int d = 0; d < 4; ++d) { O[d] = mfma32(vf[d][0], w0, O[d]); O[d] = mfma32(vf[d][1], w1, O[d]); }
	v_cndmask_b32_e64 v70, 1.0, v116, s[10:11]
	v_cndmask_b32_e64 v125, 0, v127, s[26:27]
	v_cndmask_b32_e64 v127, 0, v161, s[30:31]
	v_cndmask_b32_e64 v161, 0, v163, s[36:37]
	v_cndmask_b32_e64 v163, 0, v165, s[40:41]
	v_cndmask_b32_e64 v165, 0, v167, s[44:45]
	v_mul_f32_e32 v167, v67, v69
	v_mul_f32_e32 v69, v70, v119
	v_mul_f32_e32 v68, v68, v69
	v_mul_f32_e32 v67, v112, v68
	v_cndmask_b32_e64 v64, 0, v120, s[12:13]
	v_cndmask_b32_e64 v120, 0, v122, s[16:17]
	v_mul_f32_e32 v66, v66, v67
	v_pk_mul_f32 v[64:65], v[64:65], v[66:67]
	v_pk_mul_f32 v[66:67], v[120:121], v[68:69]
	v_mul_f32_e32 v69, v113, v117
	v_mul_f32_e32 v68, v71, v69
	v_mul_f32_e32 v71, v115, v68
	v_cndmask_b32_e64 v122, 0, v124, s[20:21]
	v_cndmask_b32_e64 v124, 0, v126, s[24:25]
	v_mul_f32_e32 v70, v114, v71
	v_pk_mul_f32 v[70:71], v[122:123], v[70:71]
	v_pk_mul_f32 v[68:69], v[124:125], v[68:69]
	v_cvt_pk_bf16_f32 v64, v64, v65
	v_cvt_pk_bf16_f32 v65, v66, v67
	v_cvt_pk_bf16_f32 v66, v70, v71
	v_cvt_pk_bf16_f32 v67, v68, v69
	v_cndmask_b32_e64 v76, 1.0, v76, s[10:11]
	v_mul_f32_e32 v113, v197, v76
	v_mfma_f32_32x32x16_bf16 v[48:63], v[108:111], v[64:67], v[48:63]
	v_cndmask_b32_e64 v126, 0, v160, s[28:29]
	v_cndmask_b32_e64 v160, 0, v162, s[34:35]
	v_cndmask_b32_e64 v162, 0, v164, s[38:39]
	v_cndmask_b32_e64 v164, 0, v166, s[42:43]
	v_mul_f32_e32 v166, v73, v167
	v_mul_f32_e32 v112, v113, v77
	v_mul_f32_e32 v75, v75, v166
	v_mfma_f32_32x32x16_bf16 v[32:47], v[96:99], v[64:67], v[32:47]
	v_mul_f32_e32 v69, v79, v112
	v_mul_f32_e32 v74, v74, v75
	v_mul_f32_e32 v68, v78, v69
	v_mul_f32_e64 v72, v160, v166
	v_mul_f32_e64 v73, v161, v167
	v_pk_mul_f32 v[74:75], v[126:127], v[74:75]
	v_pk_mul_f32 v[76:77], v[164:165], v[112:113]
	v_pk_mul_f32 v[70:71], v[162:163], v[68:69]
	v_mfma_f32_32x32x16_bf16 v[16:31], v[88:91], v[64:67], v[16:31]
	v_cvt_pk_bf16_f32 v68, v74, v75
	v_cvt_pk_bf16_f32 v69, v72, v73
	v_cvt_pk_bf16_f32 v70, v70, v71
	v_cvt_pk_bf16_f32 v71, v76, v77
	v_mfma_f32_32x32x16_bf16 v[0:15], v[84:87], v[64:67], v[0:15]
	v_mul_f32_e32 v64, v118, v116
	v_mul_f32_e32 v199, v64, v119
	v_mfma_f32_32x32x16_bf16 v[48:63], v[104:107], v[68:71], v[48:63]
	v_mfma_f32_32x32x16_bf16 v[32:47], v[100:103], v[68:71], v[32:47]
	v_mfma_f32_32x32x16_bf16 v[16:31], v[92:95], v[68:71], v[16:31]
	v_mfma_f32_32x32x16_bf16 v[0:15], v[80:83], v[68:71], v[0:15]
	s_nop 10
	v_mov_b64_e32 v[110:111], v[30:31]
	v_mov_b64_e32 v[94:95], v[46:47]
	v_mov_b64_e32 v[78:79], v[62:63]
	v_mov_b64_e32 v[108:109], v[28:29]
	v_mov_b64_e32 v[106:107], v[26:27]
	v_mov_b64_e32 v[104:105], v[24:25]
	v_mov_b64_e32 v[102:103], v[22:23]
	v_mov_b64_e32 v[126:127], v[14:15]
	v_mov_b64_e32 v[124:125], v[12:13]
	v_mov_b64_e32 v[122:123], v[10:11]
	v_mov_b64_e32 v[120:121], v[8:9]
	v_mov_b64_e32 v[118:119], v[6:7]
	v_mov_b64_e32 v[116:117], v[4:5]
	v_mov_b64_e32 v[114:115], v[2:3]
	v_mov_b64_e32 v[112:113], v[0:1]
	v_mov_b64_e32 v[100:101], v[20:21]
	v_mov_b64_e32 v[98:99], v[18:19]
	v_mov_b64_e32 v[96:97], v[16:17]
	v_mov_b64_e32 v[92:93], v[44:45]
	v_mov_b64_e32 v[90:91], v[42:43]
	v_mov_b64_e32 v[88:89], v[40:41]
	v_mov_b64_e32 v[86:87], v[38:39]
	v_mov_b64_e32 v[84:85], v[36:37]
	v_mov_b64_e32 v[82:83], v[34:35]
	v_mov_b64_e32 v[80:81], v[32:33]
	v_mov_b64_e32 v[76:77], v[60:61]
	v_mov_b64_e32 v[74:75], v[58:59]
	v_mov_b64_e32 v[72:73], v[56:57]
	v_mov_b64_e32 v[70:71], v[54:55]
	v_mov_b64_e32 v[68:69], v[52:53]
	v_mov_b64_e32 v[66:67], v[50:51]
	v_mov_b64_e32 v[64:65], v[48:49]
; DEV f32x16 mfma32(bf16x8 a, bf16x8 b, f32x16 c) { return __builtin_amdgcn_mfma_f32_32x32x16_bf16(a, b, c, 0, 0, 0); }
; template <bool DIAG>
; DEV void sb_tile(const char* lk, const char* lv, const int ko0, const int vo0, const bf16x8 (&qf)[8], f32x16 (&O)[4], float& accp,
;                  const int l31, const int hh) {
;   f32x16 z;
;   for (int g = 0; g < 16; ++g) z[g] = 0.f;
;   {
;     bf16x8 kf[8];
; #pragma unroll
;     for (int s = 0; s < 8; ++s) kf[s] = *(const bf16x8*)(lk + (ko0 ^ (32 * s)));
;     __builtin_amdgcn_sched_barrier(0);
; #pragma unroll
;     for (int s = 0; s < 8; ++s) z = mfma32(kf[s], qf[s], z);
;   }
;   bf16x8 vf[4][2];
; #pragma unroll
;   for (int d = 0; d < 4; ++d) { vf[d][0] = *(const bf16x8*)(lv + d * 4096 + vo0); vf[d][1] = *(const bf16x8*)(lv + d * 4096 + (vo0 ^ 32)); }
;   __builtin_amdgcn_sched_barrier(0);
;   float be[16], om[16];
; #pragma unroll
;   for (int g = 0; g < 16; ++g) {
;     const float e = __builtin_amdgcn_exp2f(fminf(-z[g], 120.f));
;     be[g] = __builtin_amdgcn_rcpf(1.f + e);
;     om[g] = e * be[g];
;     if (DIAG) { const int kl = (g & 3) + 8 * (g >> 2) + 4 * hh; if (kl >= l31) { be[g] = 0.f; om[g] = 1.f; } }
;   }
;   float gp[4], pp[4], tot[4];
; #pragma unroll
;   for (int q = 0; q < 4; ++q) { gp[q] = (om[4 * q] * om[4 * q + 1]) * (om[4 * q + 2] * om[4 * q + 3]); pp[q] = __shfl_xor(gp[q], 32); tot[q] = gp[q] * pp[q]; }
;   float suf[4];
;   suf[3] = accp; suf[2] = suf[3] * tot[3]; suf[1] = suf[2] * tot[2]; suf[0] = suf[1] * tot[1];
;   accp = suf[0] * tot[0];
;   f32x16 w;
; #pragma unroll
;   for (int q = 0; q < 4; ++q) {
;     float a = suf[q] * (hh == 0 ? pp[q] : 1.f);
;     w[4 * q + 3] = be[4 * q + 3] * a; a *= om[4 * q + 3];
;     w[4 * q + 2] = be[4 * q + 2] * a; a *= om[4 * q + 2];
;     w[4 * q + 1] = be[4 * q + 1] * a; a *= om[4 * q + 1];
;     w[4 * q + 0] = be[4 * q + 0] * a;
;   }
;   const bf16x8 w0 = cvt8<0>(w), w1 = cvt8<1>(w);
; #pragma unroll
;   for (int d = 0; d < 4; ++d) { O[d] = mfma32(vf[d][0], w0, O[d]); O[d] = mfma32(vf[d][1], w1, O[d]); }
.LBB0_565:
	s_cmp_lg_u32 s88, s69
	s_mov_b64 s[66:67], -1
	s_cbranch_scc0 .LBB0_569
	s_add_i32 s0, s0, 6
	s_cmp_ge_i32 s0, s75
	s_cbranch_scc1 .Lsb_skip_B0
	ds_read_b128 v[0:3], v240
	ds_read_b128 v[16:19], v241
	ds_read_b128 v[20:23], v242
	ds_read_b128 v[24:27], v243
	ds_read_b128 v[28:31], v244
	ds_read_b128 v[32:35], v245
	ds_read_b128 v[36:39], v246
	ds_read_b128 v[40:43], v247
	s_waitcnt lgkmcnt(0)
	v_mfma_f32_32x32x16_bf16 v[0:15], v[0:3], v[128:131], 0
	v_mfma_f32_32x32x16_bf16 v[0:15], v[16:19], v[132:135], v[0:15]
	v_mfma_f32_32x32x16_bf16 v[0:15], v[20:23], v[136:139], v[0:15]
	v_mfma_f32_32x32x16_bf16 v[0:15], v[24:27], v[140:143], v[0:15]
	v_mfma_f32_32x32x16_bf16 v[0:15], v[28:31], v[144:147], v[0:15]
	v_mfma_f32_32x32x16_bf16 v[0:15], v[32:35], v[148:151], v[0:15]
	ds_read_b128 v[28:31], v248
	ds_read_b128 v[16:19], v248 offset:4096
	ds_read_b128 v[24:27], v249
	ds_read_b128 v[20:23], v249 offset:4096
	ds_read_b128 v[168:171], v248 offset:8192
	ds_read_b128 v[164:167], v248 offset:12288
	ds_read_b128 v[172:175], v249 offset:8192
	ds_read_b128 v[160:163], v249 offset:12288
	v_mfma_f32_32x32x16_bf16 v[0:15], v[36:39], v[152:155], v[0:15]
	v_mfma_f32_32x32x16_bf16 v[0:15], v[40:43], v[156:159], v[0:15]
	s_nop 11
	v_min_f32_e64 v4, -v4, s32
	v_exp_f32_e32 v34, v4
	v_min_f32_e64 v4, -v5, s32
	v_exp_f32_e32 v35, v4
	v_add_f32_e32 v4, 1.0, v34
	v_min_f32_e64 v9, -v9, s32
	v_add_f32_e32 v5, 1.0, v35
	v_rcp_f32_e32 v4, v4
	v_rcp_f32_e32 v5, v5
	v_exp_f32_e32 v40, v9
	v_min_f32_e64 v9, -v10, s32
	v_min_f32_e64 v10, -v11, s32
	v_min_f32_e64 v8, -v8, s32
	v_min_f32_e64 v11, -v13, s32
	v_min_f32_e64 v13, -v15, s32
	v_exp_f32_e32 v8, v8
	v_exp_f32_e32 v41, v10
	v_min_f32_e64 v10, -v12, s32
	v_exp_f32_e32 v12, v11
	v_min_f32_e64 v11, -v14, s32
	v_pk_mul_f32 v[34:35], v[34:35], v[4:5]
	v_exp_f32_e32 v9, v9
	v_pk_mul_f32 v[14:15], v[34:35], v[34:35] op_sel_hi:[0,1]
	v_add_f32_e32 v14, 1.0, v8
	v_rcp_f32_e32 v44, v14
	v_add_f32_e32 v14, 1.0, v40
	v_rcp_f32_e32 v46, v14
	v_add_f32_e32 v14, 1.0, v9
	v_rcp_f32_e32 v45, v14
	v_add_f32_e32 v14, 1.0, v41
	v_rcp_f32_e32 v47, v14
	v_exp_f32_e32 v10, v10
	v_exp_f32_e32 v11, v11
	v_exp_f32_e32 v13, v13
	v_pk_mul_f32 v[8:9], v[8:9], v[44:45]
	v_pk_mul_f32 v[40:41], v[40:41], v[46:47]
	v_pk_mul_f32 v[48:49], v[8:9], v[40:41]
	v_add_f32_e32 v8, 1.0, v10
	v_rcp_f32_e32 v50, v8
	v_add_f32_e32 v8, 1.0, v12
	v_rcp_f32_e32 v52, v8
	v_add_f32_e32 v8, 1.0, v11
	v_min_f32_e64 v6, -v6, s32
	v_rcp_f32_e32 v51, v8
	v_add_f32_e32 v8, 1.0, v13
	v_exp_f32_e32 v36, v6
	v_rcp_f32_e32 v53, v8
	v_min_f32_e64 v6, -v7, s32
	v_min_f32_e64 v3, -v3, s32
	v_exp_f32_e32 v37, v6
	v_min_f32_e64 v0, -v0, s32
	v_exp_f32_e32 v198, v3
	v_exp_f32_e32 v32, v0
	v_pk_mul_f32 v[10:11], v[10:11], v[50:51]
	v_pk_mul_f32 v[12:13], v[12:13], v[52:53]
	v_add_f32_e32 v6, 1.0, v36
	v_pk_mul_f32 v[54:55], v[10:11], v[12:13]
	v_add_f32_e32 v7, 1.0, v37
	v_mul_f32_e32 v8, v54, v55
	v_add_f32_e32 v3, 1.0, v198
	v_rcp_f32_e32 v6, v6
	v_rcp_f32_e32 v7, v7
	v_pk_mul_f32 v[48:49], v[48:49], v[48:49] op_sel:[0,1] op_sel_hi:[1,0]
	v_mov_b32_e32 v10, v8
	s_nop 1
	v_permlane32_swap_b32_e32 v8, v10
	v_add_f32_e32 v0, 1.0, v32
	v_min_f32_e64 v2, -v2, s32
	v_rcp_f32_e32 v3, v3
	v_mov_b32_e32 v49, v48
	s_nop 1
	v_permlane32_swap_b32_e32 v48, v49
	v_rcp_f32_e32 v0, v0
	v_min_f32_e64 v1, -v1, s32
	v_exp_f32_e32 v38, v2
	v_exp_f32_e32 v56, v1
	v_pk_mul_f32 v[36:37], v[36:37], v[6:7]
	s_waitcnt lgkmcnt(0)
	v_mul_f32_e32 v55, v8, v10
	v_pk_mul_f32 v[42:43], v[36:37], v[36:37] op_sel_hi:[0,1]
	v_mov_b32_e32 v54, v3
	v_add_f32_e32 v2, 1.0, v38
	v_mov_b32_e32 v33, v15
	v_cndmask_b32_e64 v8, 1.0, v49, s[10:11]
	v_mov_b32_e32 v14, v45
	v_mov_b32_e32 v15, v47
	v_mov_b32_e32 v45, v46
	v_pk_mul_f32 v[46:47], v[198:199], v[54:55]
	v_mov_b32_e32 v42, v0
	v_add_f32_e32 v1, 1.0, v56
	v_rcp_f32_e32 v2, v2
	v_mul_f32_e32 v55, v8, v47
	v_pk_mul_f32 v[32:33], v[32:33], v[42:43]
	v_rcp_f32_e32 v1, v1
	v_mul_f32_e32 v54, v41, v55
	v_mov_b32_e32 v41, v33
	s_nop 1
	v_permlane32_swap_b32_e32 v33, v41
	v_mov_b32_e32 v39, v48
	v_mov_b32_e32 v48, v2
	v_mul_f32_e32 v9, v9, v54
	v_pk_mul_f32 v[38:39], v[38:39], v[48:49]
	v_mul_f32_e32 v8, v40, v9
	v_mul_f32_e32 v40, v56, v1
	v_pk_mul_f32 v[48:49], v[38:39], v[46:47]
	s_waitcnt lgkmcnt(0)
	v_pk_mul_f32 v[32:33], v[32:33], v[40:41]
	v_cndmask_b32_e64 v34, 1.0, v41, s[10:11]
	v_pk_mul_f32 v[32:33], v[32:33], v[48:49]
	v_mov_b32_e32 v39, v32
	s_nop 1
	v_permlane32_swap_b32_e32 v32, v39
	v_cndmask_b32_e64 v10, 1.0, v10, s[10:11]
	v_pk_mul_f32 v[14:15], v[14:15], v[54:55]
	v_pk_mul_f32 v[8:9], v[44:45], v[8:9]
	v_cvt_pk_bf16_f32 v225, v14, v15
	s_waitcnt lgkmcnt(0)
	v_mul_f32_e32 v32, v32, v39
	v_mul_f32_e32 v197, v32, v33
	v_cndmask_b32_e64 v32, 1.0, v39, s[10:11]
	v_mul_f32_e32 v33, v32, v33
	v_mul_f32_e32 v32, v46, v33
	v_pk_mul_f32 v[2:3], v[2:3], v[32:33]
	v_mul_f32_e32 v33, v34, v49
	v_mul_f32_e32 v39, v38, v32
	v_mul_f32_e32 v32, v37, v33
	v_mul_f32_e32 v37, v36, v32
	v_mul_f32_e32 v36, v35, v37
	v_mul_f32_e32 v35, v199, v10
	v_mul_f32_e32 v38, v40, v39
	v_mul_f32_e32 v34, v13, v35
	v_pk_mul_f32 v[0:1], v[0:1], v[38:39]
	v_pk_mul_f32 v[4:5], v[4:5], v[36:37]
	v_pk_mul_f32 v[6:7], v[6:7], v[32:33]
	v_mov_b32_e32 v32, v51
	v_mov_b32_e32 v33, v53
	v_mul_f32_e32 v11, v11, v34
	v_pk_mul_f32 v[32:33], v[32:33], v[34:35]
	v_mov_b32_e32 v51, v52
	v_mul_f32_e32 v10, v12, v11
	v_cvt_pk_bf16_f32 v214, v0, v1
	v_cvt_pk_bf16_f32 v215, v2, v3
	v_cvt_pk_bf16_f32 v216, v4, v5
	v_cvt_pk_bf16_f32 v217, v6, v7
	v_pk_mul_f32 v[10:11], v[50:51], v[10:11]
	v_cvt_pk_bf16_f32 v227, v32, v33
	v_mfma_f32_32x32x16_bf16 v[48:63], v[28:31], v[214:217], v[64:79]
	v_cvt_pk_bf16_f32 v224, v8, v9
	v_cvt_pk_bf16_f32 v226, v10, v11
	v_mfma_f32_32x32x16_bf16 v[32:47], v[16:19], v[214:217], v[80:95]
	s_nop 0
	v_mfma_f32_32x32x16_bf16 v[48:63], v[24:27], v[224:227], v[48:63]
	v_mfma_f32_32x32x16_bf16 v[32:47], v[20:23], v[224:227], v[32:47]
	v_mfma_f32_32x32x16_bf16 v[16:31], v[168:171], v[214:217], v[96:111]
	v_mfma_f32_32x32x16_bf16 v[0:15], v[164:167], v[214:217], v[112:127]
	v_mfma_f32_32x32x16_bf16 v[16:31], v[172:175], v[224:227], v[16:31]
	v_mfma_f32_32x32x16_bf16 v[0:15], v[160:163], v[224:227], v[0:15]

; DEV f32x16 mfma32(bf16x8 a, bf16x8 b, f32x16 c) { return __builtin_amdgcn_mfma_f32_32x32x16_bf16(a, b, c, 0, 0, 0); }
; template <bool DIAG>
; DEV void sb_tile(const char* lk, const char* lv, const int ko0, const int vo0, const bf16x8 (&qf)[8], f32x16 (&O)[4], float& accp,
;                  const int l31, const int hh) {
;   f32x16 z;
;   for (int g = 0; g < 16; ++g) z[g] = 0.f;
;   {
;     bf16x8 kf[8];
; #pragma unroll
;     for (int s = 0; s < 8; ++s) kf[s] = *(const bf16x8*)(lk + (ko0 ^ (32 * s)));
;     __builtin_amdgcn_sched_barrier(0);
; #pragma unroll
;     for (int s = 0; s < 8; ++s) z = mfma32(kf[s], qf[s], z);
;   }
;   bf16x8 vf[4][2];
; #pragma unroll
;   for (int d = 0; d < 4; ++d) { vf[d][0] = *(const bf16x8*)(lv + d * 4096 + vo0); vf[d][1] = *(const bf16x8*)(lv + d * 4096 + (vo0 ^ 32)); }
;   __builtin_amdgcn_sched_barrier(0);
;   float be[16], om[16];
; #pragma unroll
;   for (int g = 0; g < 16; ++g) {
;     const float e = __builtin_amdgcn_exp2f(fminf(-z[g], 120.f));
;     be[g] = __builtin_amdgcn_rcpf(1.f + e);
;     om[g] = e * be[g];
;     if (DIAG) { const int kl = (g & 3) + 8 * (g >> 2) + 4 * hh; if (kl >= l31) { be[g] = 0.f; om[g] = 1.f; } }
;   }
;   float gp[4], pp[4], tot[4];
; #pragma unroll
;   for (int q = 0; q < 4; ++q) { gp[q] = (om[4 * q] * om[4 * q + 1]) * (om[4 * q + 2] * om[4 * q + 3]); pp[q] = __shfl_xor(gp[q], 32); tot[q] = gp[q] * pp[q]; }
;   float suf[4];
;   suf[3] = accp; suf[2] = suf[3] * tot[3]; suf[1] = suf[2] * tot[2]; suf[0] = suf[1] * tot[1];
.LBB0_570:
	s_nop 9
	ds_read_b128 v[0:3], v240
	ds_read_b128 v[16:19], v241
	ds_read_b128 v[20:23], v242
	ds_read_b128 v[24:27], v243
	ds_read_b128 v[28:31], v244
	ds_read_b128 v[32:35], v245
	ds_read_b128 v[36:39], v246
	ds_read_b128 v[48:51], v247
	s_waitcnt lgkmcnt(0)
	v_mfma_f32_32x32x16_bf16 v[0:15], v[0:3], v[128:131], 0
	v_mfma_f32_32x32x16_bf16 v[0:15], v[16:19], v[132:135], v[0:15]
	v_mfma_f32_32x32x16_bf16 v[0:15], v[20:23], v[136:139], v[0:15]
	v_mfma_f32_32x32x16_bf16 v[0:15], v[24:27], v[140:143], v[0:15]
	v_mfma_f32_32x32x16_bf16 v[0:15], v[28:31], v[144:147], v[0:15]
	v_mfma_f32_32x32x16_bf16 v[0:15], v[32:35], v[148:151], v[0:15]
	v_mfma_f32_32x32x16_bf16 v[0:15], v[36:39], v[152:155], v[0:15]
	ds_read_b128 v[44:47], v248
	ds_read_b128 v[32:35], v248 offset:4096
	ds_read_b128 v[40:43], v249
	ds_read_b128 v[36:39], v249 offset:4096
	ds_read_b128 v[24:27], v248 offset:8192
	ds_read_b128 v[20:23], v248 offset:12288
	ds_read_b128 v[28:31], v249 offset:8192
	ds_read_b128 v[16:19], v249 offset:12288
	v_mfma_f32_32x32x16_bf16 v[0:15], v[48:51], v[156:159], v[0:15]
	s_nop 11
	v_min_f32_e64 v0, -v0, s32
	v_exp_f32_e32 v0, v0
	v_min_f32_e64 v1, -v1, s32
	v_exp_f32_e32 v1, v1
	v_add_f32_e32 v48, 1.0, v0
	v_rcp_f32_e32 v56, v48
	v_add_f32_e32 v48, 1.0, v1
	v_min_f32_e64 v2, -v2, s32
	v_rcp_f32_e32 v57, v48
	v_exp_f32_e32 v48, v2
	v_min_f32_e64 v2, -v3, s32
	v_exp_f32_e32 v3, v2
	v_add_f32_e32 v2, 1.0, v48
	v_rcp_f32_e32 v58, v2
	v_mul_f32_e32 v1, v1, v57
	v_add_f32_e32 v2, 1.0, v3
	v_rcp_f32_e32 v59, v2
	v_cndmask_b32_e64 v2, 1.0, v1, s[14:15]
	v_mul_f32_e32 v1, v48, v58
	v_cndmask_b32_e64 v48, 1.0, v1, s[16:17]
	v_mul_f32_e32 v1, v3, v59
	v_min_f32_e64 v3, -v4, s32
	v_exp_f32_e32 v3, v3
	v_min_f32_e64 v4, -v5, s32
	v_exp_f32_e32 v5, v4
	v_cndmask_b32_e64 v4, 1.0, v1, s[18:19]
	v_add_f32_e32 v1, 1.0, v3
	v_rcp_f32_e32 v60, v1
	v_add_f32_e32 v1, 1.0, v5
	v_rcp_f32_e32 v61, v1
	v_min_f32_e64 v1, -v6, s32
	v_exp_f32_e32 v1, v1
	v_mul_f32_e32 v3, v3, v60
	v_cndmask_b32_e64 v6, 1.0, v3, s[20:21]
	v_mul_f32_e32 v3, v5, v61
	v_add_f32_e32 v5, 1.0, v1
	v_rcp_f32_e32 v62, v5
	v_min_f32_e64 v5, -v7, s32
	v_exp_f32_e32 v5, v5
	v_mul_f32_e32 v1, v1, v62
	v_cndmask_b32_e64 v51, 1.0, v1, s[24:25]
	v_cndmask_b32_e64 v50, 1.0, v3, s[22:23]
	v_add_f32_e32 v1, 1.0, v5
	v_rcp_f32_e32 v63, v1
	v_min_f32_e64 v1, -v8, s32
	v_exp_f32_e32 v1, v1
	v_min_f32_e64 v3, -v9, s32
	v_exp_f32_e32 v3, v3
	v_mul_f32_e32 v5, v5, v63
	v_add_f32_e32 v7, 1.0, v1
	v_rcp_f32_e32 v160, v7
	v_add_f32_e32 v7, 1.0, v3
	v_rcp_f32_e32 v161, v7
	v_cndmask_b32_e64 v7, 1.0, v5, s[26:27]
	v_mul_f32_e32 v1, v1, v160
	v_cndmask_b32_e64 v8, 1.0, v1, s[28:29]
	v_mul_f32_e32 v1, v3, v161
	v_min_f32_e64 v3, -v10, s32
	v_exp_f32_e32 v3, v3
	v_min_f32_e64 v5, -v11, s32
	v_exp_f32_e32 v5, v5
	v_cndmask_b32_e64 v10, 1.0, v1, s[30:31]
	v_add_f32_e32 v1, 1.0, v3
	v_rcp_f32_e32 v162, v1
	v_add_f32_e32 v1, 1.0, v5
	v_rcp_f32_e32 v163, v1
	v_min_f32_e64 v1, -v12, s32
	v_exp_f32_e32 v1, v1
	v_mul_f32_e32 v3, v3, v162
	v_cndmask_b32_e64 v11, 1.0, v3, s[34:35]
	v_mul_f32_e32 v3, v5, v163
	v_add_f32_e32 v5, 1.0, v1
	v_rcp_f32_e32 v164, v5
	v_min_f32_e64 v5, -v13, s32
	v_exp_f32_e32 v5, v5
	v_mul_f32_e32 v1, v1, v164
	v_cndmask_b32_e64 v12, 1.0, v1, s[38:39]
	v_cndmask_b32_e64 v9, 1.0, v3, s[36:37]
	v_add_f32_e32 v1, 1.0, v5
	v_rcp_f32_e32 v165, v1
	v_min_f32_e64 v1, -v14, s32
	v_exp_f32_e32 v1, v1
	v_min_f32_e64 v3, -v15, s32
	v_exp_f32_e32 v3, v3
	v_mul_f32_e32 v5, v5, v165
	v_add_f32_e32 v13, 1.0, v1
	v_rcp_f32_e32 v166, v13
	v_add_f32_e32 v13, 1.0, v3
	v_rcp_f32_e32 v167, v13
	v_cndmask_b32_e64 v14, 1.0, v5, s[40:41]
	v_mul_f32_e32 v1, v1, v166
	v_cndmask_b32_e64 v15, 1.0, v1, s[42:43]
	v_mul_f32_e32 v1, v3, v167
	v_cndmask_b32_e64 v13, 1.0, v1, s[44:45]
	v_pk_mul_f32 v[52:53], v[10:11], v[8:9]
	v_mul_f32_e32 v0, v0, v56
	v_mul_f32_e32 v1, v52, v53
	v_pk_mul_f32 v[52:53], v[14:15], v[12:13]
	v_mov_b32_e32 v8, v1
	s_nop 1
	v_permlane32_swap_b32_e32 v1, v8
	v_mul_f32_e32 v5, v52, v53
	v_mov_b32_e32 v12, v5
	s_nop 1
	v_permlane32_swap_b32_e32 v5, v12
	v_pk_mul_f32 v[52:53], v[50:51], v[6:7]
	v_cndmask_b32_e64 v0, 1.0, v0, s[12:13]
	v_pk_mul_f32 v[52:53], v[52:53], v[52:53] op_sel:[0,1] op_sel_hi:[1,0]
	v_mov_b32_e32 v3, v52
	s_nop 1
	v_permlane32_swap_b32_e32 v52, v3
	s_waitcnt lgkmcnt(0)
	v_mul_f32_e32 v49, v1, v8
	v_mul_f32_e32 v1, v5, v12
	v_mul_f32_e32 v5, v199, v1
	v_mov_b32_e32 v1, v52
	v_pk_mul_f32 v[0:1], v[0:1], v[2:3]
	v_pk_mul_f32 v[52:53], v[48:49], v[4:5]
	v_cndmask_b32_e64 v49, 1.0, v3, s[10:11]
	v_pk_mul_f32 v[54:55], v[0:1], v[52:53]
	v_mov_b32_e32 v52, v54
	s_nop 1
	v_permlane32_swap_b32_e32 v54, v52
	v_cndmask_b32_e64 v3, 1.0, v8, s[10:11]
	v_cndmask_b32_e64 v1, 0, v57, s[14:15]
	v_cndmask_b32_e64 v57, 0, v59, s[18:19]
	v_cndmask_b32_e64 v59, 0, v61, s[22:23]
	s_waitcnt lgkmcnt(0)
; DEV f32x16 mfma32(bf16x8 a, bf16x8 b, f32x16 c) { return __builtin_amdgcn_mfma_f32_32x32x16_bf16(a, b, c, 0, 0, 0); }
; template <bool DIAG>
; DEV void sb_tile(const char* lk, const char* lv, const int ko0, const int vo0, const bf16x8 (&qf)[8], f32x16 (&O)[4], float& accp,
;                  const int l31, const int hh) {
;     ...
;     if (DIAG) { const int kl = (g & 3) + 8 * (g >> 2) + 4 * hh; if (kl >= l31) { be[g] = 0.f; om[g] = 1.f; } }
;   }
;   float gp[4], pp[4], tot[4];
; #pragma unroll
;   for (int q = 0; q < 4; ++q) { gp[q] = (om[4 * q] * om[4 * q + 1]) * (om[4 * q + 2] * om[4 * q + 3]); pp[q] = __shfl_xor(gp[q], 32); tot[q] = gp[q] * pp[q]; }
;   float suf[4];
;   suf[3] = accp; suf[2] = suf[3] * tot[3]; suf[1] = suf[2] * tot[2]; suf[0] = suf[1] * tot[1];
;   accp = suf[0] * tot[0];
;   f32x16 w;
; #pragma unroll
;   for (int q = 0; q < 4; ++q) {
;     float a = suf[q] * (hh == 0 ? pp[q] : 1.f);
;     w[4 * q + 3] = be[4 * q + 3] * a; a *= om[4 * q + 3];
;     w[4 * q + 2] = be[4 * q + 2] * a; a *= om[4 * q + 2];
;     w[4 * q + 1] = be[4 * q + 1] * a; a *= om[4 * q + 1];
;     w[4 * q + 0] = be[4 * q + 0] * a;
;   }
;   const bf16x8 w0 = cvt8<0>(w), w1 = cvt8<1>(w);
; #pragma unroll
;   for (int d = 0; d < 4; ++d) { O[d] = mfma32(vf[d][0], w0, O[d]); O[d] = mfma32(vf[d][1], w1, O[d]); }
	v_cndmask_b32_e64 v6, 1.0, v52, s[10:11]
	v_cndmask_b32_e64 v61, 0, v63, s[26:27]
	v_cndmask_b32_e64 v63, 0, v161, s[30:31]
	v_cndmask_b32_e64 v161, 0, v163, s[36:37]
	v_cndmask_b32_e64 v163, 0, v165, s[40:41]
	v_cndmask_b32_e64 v165, 0, v167, s[44:45]
	v_mul_f32_e32 v167, v3, v5
	v_mul_f32_e32 v5, v6, v55
	v_mul_f32_e32 v4, v4, v5
	v_mul_f32_e32 v3, v48, v4
	v_cndmask_b32_e64 v0, 0, v56, s[12:13]
	v_cndmask_b32_e64 v56, 0, v58, s[16:17]
	v_mul_f32_e32 v2, v2, v3
	v_pk_mul_f32 v[0:1], v[0:1], v[2:3]
	v_pk_mul_f32 v[2:3], v[56:57], v[4:5]
	v_mul_f32_e32 v5, v49, v53
	v_mul_f32_e32 v4, v7, v5
	v_mul_f32_e32 v7, v51, v4
	v_cndmask_b32_e64 v58, 0, v60, s[20:21]
	v_cndmask_b32_e64 v60, 0, v62, s[24:25]
	v_mul_f32_e32 v6, v50, v7
	v_pk_mul_f32 v[6:7], v[58:59], v[6:7]
	v_pk_mul_f32 v[4:5], v[60:61], v[4:5]
	v_cvt_pk_bf16_f32 v0, v0, v1
	v_cvt_pk_bf16_f32 v1, v2, v3
	v_cvt_pk_bf16_f32 v2, v6, v7
	v_cvt_pk_bf16_f32 v3, v4, v5
	v_cndmask_b32_e64 v12, 1.0, v12, s[10:11]
	v_mul_f32_e32 v49, v199, v12
	v_mfma_f32_32x32x16_bf16 v[64:79], v[44:47], v[0:3], v[64:79]
	v_cndmask_b32_e64 v62, 0, v160, s[28:29]
	v_cndmask_b32_e64 v160, 0, v162, s[34:35]
	v_cndmask_b32_e64 v162, 0, v164, s[38:39]
	v_cndmask_b32_e64 v164, 0, v166, s[42:43]
	v_mul_f32_e32 v166, v9, v167
	v_mul_f32_e32 v48, v49, v13
	v_mul_f32_e32 v11, v11, v166
	v_mfma_f32_32x32x16_bf16 v[80:95], v[32:35], v[0:3], v[80:95]
	v_mul_f32_e32 v5, v15, v48
	v_mul_f32_e32 v10, v10, v11
	v_mul_f32_e32 v4, v14, v5
	v_mul_f32_e64 v8, v160, v166
	v_mul_f32_e64 v9, v161, v167
	v_pk_mul_f32 v[10:11], v[62:63], v[10:11]
	v_pk_mul_f32 v[12:13], v[164:165], v[48:49]
	v_pk_mul_f32 v[6:7], v[162:163], v[4:5]
	v_mfma_f32_32x32x16_bf16 v[96:111], v[24:27], v[0:3], v[96:111]
	v_cvt_pk_bf16_f32 v4, v10, v11
	v_cvt_pk_bf16_f32 v5, v8, v9
	v_cvt_pk_bf16_f32 v6, v6, v7
	v_cvt_pk_bf16_f32 v7, v12, v13
	v_mfma_f32_32x32x16_bf16 v[112:127], v[20:23], v[0:3], v[112:127]
	v_mul_f32_e32 v0, v54, v52
	v_mul_f32_e32 v197, v0, v55
	v_mfma_f32_32x32x16_bf16 v[64:79], v[40:43], v[4:7], v[64:79]
	v_mfma_f32_32x32x16_bf16 v[80:95], v[36:39], v[4:7], v[80:95]
	s_nop 10
	v_mov_b64_e32 v[48:49], v[64:65]
	v_mov_b64_e32 v[50:51], v[66:67]
	v_mov_b64_e32 v[52:53], v[68:69]
	v_mov_b64_e32 v[54:55], v[70:71]
	v_mov_b64_e32 v[56:57], v[72:73]
	v_mov_b64_e32 v[58:59], v[74:75]
	v_mov_b64_e32 v[60:61], v[76:77]
	v_mfma_f32_32x32x16_bf16 v[96:111], v[28:31], v[4:7], v[96:111]
	v_mov_b64_e32 v[32:33], v[80:81]
	v_mov_b64_e32 v[34:35], v[82:83]
	v_mov_b64_e32 v[36:37], v[84:85]
	v_mov_b64_e32 v[38:39], v[86:87]
	v_mov_b64_e32 v[40:41], v[88:89]
	v_mov_b64_e32 v[42:43], v[90:91]
	v_mov_b64_e32 v[44:45], v[92:93]
	v_mfma_f32_32x32x16_bf16 v[112:127], v[16:19], v[4:7], v[112:127]
	s_nop 3
	v_mov_b64_e32 v[16:17], v[96:97]
	v_mov_b64_e32 v[18:19], v[98:99]
	v_mov_b64_e32 v[20:21], v[100:101]
	v_mov_b64_e32 v[22:23], v[102:103]
	v_mov_b64_e32 v[24:25], v[104:105]
	v_mov_b64_e32 v[26:27], v[106:107]
	v_mov_b64_e32 v[28:29], v[108:109]
	s_nop 0
	v_mov_b64_e32 v[0:1], v[112:113]
	v_mov_b64_e32 v[2:3], v[114:115]
	v_mov_b64_e32 v[4:5], v[116:117]
	v_mov_b64_e32 v[6:7], v[118:119]
	v_mov_b64_e32 v[8:9], v[120:121]
	v_mov_b64_e32 v[10:11], v[122:123]
	v_mov_b64_e32 v[12:13], v[124:125]
	v_mov_b64_e32 v[14:15], v[126:127]
	v_mov_b64_e32 v[30:31], v[110:111]
	v_mov_b64_e32 v[46:47], v[94:95]
	v_mov_b64_e32 v[62:63], v[78:79]
	s_branch .LBB0_542
.Lsb_skip_A0:
	v_mov_b64_e32 v[78:79], v[62:63]
	v_mov_b64_e32 v[94:95], v[46:47]
	v_mov_b64_e32 v[110:111], v[30:31]
	v_mov_b64_e32 v[126:127], v[14:15]
	v_mov_b32_e32 v199, v197
	v_mov_b64_e32 v[76:77], v[60:61]
	v_mov_b64_e32 v[74:75], v[58:59]
	v_mov_b64_e32 v[72:73], v[56:57]
	v_mov_b64_e32 v[70:71], v[54:55]
	v_mov_b64_e32 v[68:69], v[52:53]
	v_mov_b64_e32 v[66:67], v[50:51]
	v_mov_b64_e32 v[64:65], v[48:49]
	v_mov_b64_e32 v[92:93], v[44:45]
	v_mov_b64_e32 v[90:91], v[42:43]
	v_mov_b64_e32 v[88:89], v[40:41]
	v_mov_b64_e32 v[86:87], v[38:39]
	v_mov_b64_e32 v[84:85], v[36:37]
	v_mov_b64_e32 v[82:83], v[34:35]
	v_mov_b64_e32 v[80:81], v[32:33]
	v_mov_b64_e32 v[108:109], v[28:29]
	v_mov_b64_e32 v[106:107], v[26:27]
	v_mov_b64_e32 v[104:105], v[24:25]
	v_mov_b64_e32 v[102:103], v[22:23]
	v_mov_b64_e32 v[100:101], v[20:21]
	v_mov_b64_e32 v[98:99], v[18:19]
	v_mov_b64_e32 v[96:97], v[16:17]
	v_mov_b64_e32 v[124:125], v[12:13]
	v_mov_b64_e32 v[122:123], v[10:11]
	v_mov_b64_e32 v[120:121], v[8:9]
	v_mov_b64_e32 v[118:119], v[6:7]
	v_mov_b64_e32 v[116:117], v[4:5]
	v_mov_b64_e32 v[114:115], v[2:3]
	v_mov_b64_e32 v[112:113], v[0:1]
	s_branch .LBB0_562
	s_nop 0
	s_nop 0
	s_nop 0
	s_nop 0
	s_nop 0
	s_nop 0
	s_nop 0
	s_nop 0
	s_nop 0
	s_nop 0
	s_nop 0
	s_nop 0
	s_nop 0
	s_nop 0
	s_nop 0
	s_nop 0
	s_nop 0
	s_nop 0
	s_nop 0
	s_nop 0
	s_nop 0
	s_nop 0
	s_nop 0
	s_nop 0
	s_nop 0
	s_nop 0
	s_nop 0
	s_nop 0
	s_nop 0
	s_nop 0
	s_nop 0
	s_nop 0
	s_nop 0
	s_nop 0
	s_nop 0
	s_nop 0
	s_nop 0
	s_nop 0
	s_nop 0
	s_nop 0
	s_nop 0
	s_nop 0
	s_nop 0
	s_nop 0
	s_nop 0
	s_nop 0
	s_nop 0
	s_nop 0
	s_nop 0
	s_nop 0
	s_nop 0
	s_nop 0
	s_nop 0
	s_nop 0
	s_nop 0
	s_nop 0
	s_nop 0
	s_nop 0
	s_nop 0
	s_nop 0
	s_nop 0
	s_nop 0
	s_nop 0
	s_nop 0
	s_nop 0
	s_nop 0
	s_nop 0
	s_nop 0
	s_nop 0
	s_nop 0
	s_nop 0
	s_nop 0

; DEV f32x16 mfma32(bf16x8 a, bf16x8 b, f32x16 c) { return __builtin_amdgcn_mfma_f32_32x32x16_bf16(a, b, c, 0, 0, 0); }
; template <bool DIAG>
; DEV void sb_tile(const char* lk, const char* lv, const int ko0, const int vo0, const bf16x8 (&qf)[8], f32x16 (&O)[4], float& accp,
;                  const int l31, const int hh) {
;   f32x16 z;
;   for (int g = 0; g < 16; ++g) z[g] = 0.f;
;   {
;     bf16x8 kf[8];
; #pragma unroll
;     for (int s = 0; s < 8; ++s) kf[s] = *(const bf16x8*)(lk + (ko0 ^ (32 * s)));
;     __builtin_amdgcn_sched_barrier(0);
; #pragma unroll
;     for (int s = 0; s < 8; ++s) z = mfma32(kf[s], qf[s], z);
;   }
;   bf16x8 vf[4][2];
; #pragma unroll
;   for (int d = 0; d < 4; ++d) { vf[d][0] = *(const bf16x8*)(lv + d * 4096 + vo0); vf[d][1] = *(const bf16x8*)(lv + d * 4096 + (vo0 ^ 32)); }
;   __builtin_amdgcn_sched_barrier(0);
;   float be[16], om[16];
; #pragma unroll
;   for (int g = 0; g < 16; ++g) {
;     const float e = __builtin_amdgcn_exp2f(fminf(-z[g], 120.f));
;     be[g] = __builtin_amdgcn_rcpf(1.f + e);
;     om[g] = e * be[g];
;     if (DIAG) { const int kl = (g & 3) + 8 * (g >> 2) + 4 * hh; if (kl >= l31) { be[g] = 0.f; om[g] = 1.f; } }
;   }
;   float gp[4], pp[4], tot[4];
; #pragma unroll
;   for (int q = 0; q < 4; ++q) { gp[q] = (om[4 * q] * om[4 * q + 1]) * (om[4 * q + 2] * om[4 * q + 3]); pp[q] = __shfl_xor(gp[q], 32); tot[q] = gp[q] * pp[q]; }
;   float suf[4];
;   suf[3] = accp; suf[2] = suf[3] * tot[3]; suf[1] = suf[2] * tot[2]; suf[0] = suf[1] * tot[1];
;   accp = suf[0] * tot[0];
;   f32x16 w;
; #pragma unroll
;   for (int q = 0; q < 4; ++q) {
;     float a = suf[q] * (hh == 0 ? pp[q] : 1.f);
;     w[4 * q + 3] = be[4 * q + 3] * a; a *= om[4 * q + 3];
;     w[4 * q + 2] = be[4 * q + 2] * a; a *= om[4 * q + 2];
;     w[4 * q + 1] = be[4 * q + 1] * a; a *= om[4 * q + 1];
;     w[4 * q + 0] = be[4 * q + 0] * a;
;   }
;   const bf16x8 w0 = cvt8<0>(w), w1 = cvt8<1>(w);
; #pragma unroll
;   for (int d = 0; d < 4; ++d) { O[d] = mfma32(vf[d][0], w0, O[d]); O[d] = mfma32(vf[d][1], w1, O[d]); }
.LBB0_1217:
	s_cmp_lg_u32 s88, s69
	s_mov_b64 s[66:67], -1
	s_cbranch_scc0 .LBB0_1221
	s_add_i32 s90, s90, 6
	s_cmp_ge_i32 s90, s76
	s_cbranch_scc1 .Lsb_skip_B1
	ds_read_b128 v[0:3], v240
	ds_read_b128 v[16:19], v241
	ds_read_b128 v[20:23], v242
	ds_read_b128 v[24:27], v243
	ds_read_b128 v[28:31], v244
	ds_read_b128 v[32:35], v245
	ds_read_b128 v[36:39], v246
	ds_read_b128 v[40:43], v247
	s_waitcnt lgkmcnt(0)
	v_mfma_f32_32x32x16_bf16 v[0:15], v[0:3], v[128:131], 0
	v_mfma_f32_32x32x16_bf16 v[0:15], v[16:19], v[132:135], v[0:15]
	v_mfma_f32_32x32x16_bf16 v[0:15], v[20:23], v[136:139], v[0:15]
	v_mfma_f32_32x32x16_bf16 v[0:15], v[24:27], v[140:143], v[0:15]
	v_mfma_f32_32x32x16_bf16 v[0:15], v[28:31], v[144:147], v[0:15]
	v_mfma_f32_32x32x16_bf16 v[0:15], v[32:35], v[148:151], v[0:15]
	ds_read_b128 v[28:31], v248
	ds_read_b128 v[16:19], v248 offset:4096
	ds_read_b128 v[24:27], v249
	ds_read_b128 v[20:23], v249 offset:4096
	ds_read_b128 v[168:171], v248 offset:8192
	ds_read_b128 v[164:167], v248 offset:12288
	ds_read_b128 v[172:175], v249 offset:8192
	ds_read_b128 v[160:163], v249 offset:12288
	v_mfma_f32_32x32x16_bf16 v[0:15], v[36:39], v[152:155], v[0:15]
	v_mfma_f32_32x32x16_bf16 v[0:15], v[40:43], v[156:159], v[0:15]
	s_nop 11
	v_min_f32_e64 v4, -v4, s32
	v_exp_f32_e32 v34, v4
	v_min_f32_e64 v4, -v5, s32
	v_exp_f32_e32 v35, v4
	v_add_f32_e32 v4, 1.0, v34
	v_min_f32_e64 v9, -v9, s32
	v_add_f32_e32 v5, 1.0, v35
	v_rcp_f32_e32 v4, v4
	v_rcp_f32_e32 v5, v5
	v_exp_f32_e32 v40, v9
	v_min_f32_e64 v9, -v10, s32
	v_min_f32_e64 v10, -v11, s32
	v_min_f32_e64 v8, -v8, s32
	v_min_f32_e64 v11, -v13, s32
	v_min_f32_e64 v13, -v15, s32
	v_exp_f32_e32 v8, v8
	v_exp_f32_e32 v41, v10
	v_min_f32_e64 v10, -v12, s32
	v_exp_f32_e32 v12, v11
	v_min_f32_e64 v11, -v14, s32
	v_pk_mul_f32 v[34:35], v[34:35], v[4:5]
	v_exp_f32_e32 v9, v9
	v_pk_mul_f32 v[14:15], v[34:35], v[34:35] op_sel_hi:[0,1]
	v_add_f32_e32 v14, 1.0, v8
	v_rcp_f32_e32 v44, v14
	v_add_f32_e32 v14, 1.0, v40
	v_rcp_f32_e32 v46, v14
	v_add_f32_e32 v14, 1.0, v9
	v_rcp_f32_e32 v45, v14
	v_add_f32_e32 v14, 1.0, v41
	v_rcp_f32_e32 v47, v14
	v_exp_f32_e32 v10, v10
	v_exp_f32_e32 v11, v11
	v_exp_f32_e32 v13, v13
	v_pk_mul_f32 v[8:9], v[8:9], v[44:45]
	v_pk_mul_f32 v[40:41], v[40:41], v[46:47]
	v_pk_mul_f32 v[48:49], v[8:9], v[40:41]
	v_add_f32_e32 v8, 1.0, v10
	v_rcp_f32_e32 v50, v8
	v_add_f32_e32 v8, 1.0, v12
	v_rcp_f32_e32 v52, v8
	v_add_f32_e32 v8, 1.0, v11
	v_min_f32_e64 v6, -v6, s32
	v_rcp_f32_e32 v51, v8
	v_add_f32_e32 v8, 1.0, v13
	v_exp_f32_e32 v36, v6
	v_rcp_f32_e32 v53, v8
	v_min_f32_e64 v6, -v7, s32
	v_min_f32_e64 v3, -v3, s32
	v_exp_f32_e32 v37, v6
	v_min_f32_e64 v0, -v0, s32
	v_exp_f32_e32 v198, v3
	v_exp_f32_e32 v32, v0
	v_pk_mul_f32 v[10:11], v[10:11], v[50:51]
	v_pk_mul_f32 v[12:13], v[12:13], v[52:53]
	v_add_f32_e32 v6, 1.0, v36
	v_pk_mul_f32 v[54:55], v[10:11], v[12:13]
	v_add_f32_e32 v7, 1.0, v37
	v_mul_f32_e32 v8, v54, v55
	v_add_f32_e32 v3, 1.0, v198
	v_rcp_f32_e32 v6, v6
	v_rcp_f32_e32 v7, v7
	v_pk_mul_f32 v[48:49], v[48:49], v[48:49] op_sel:[0,1] op_sel_hi:[1,0]
	v_mov_b32_e32 v10, v8
	s_nop 1
	v_permlane32_swap_b32_e32 v8, v10
	v_add_f32_e32 v0, 1.0, v32
	v_min_f32_e64 v2, -v2, s32
	v_rcp_f32_e32 v3, v3
	v_mov_b32_e32 v49, v48
	s_nop 1
	v_permlane32_swap_b32_e32 v48, v49
	v_rcp_f32_e32 v0, v0
	v_min_f32_e64 v1, -v1, s32
	v_exp_f32_e32 v38, v2
	v_exp_f32_e32 v56, v1
	v_pk_mul_f32 v[36:37], v[36:37], v[6:7]
	s_waitcnt lgkmcnt(0)
	v_mul_f32_e32 v55, v8, v10
	v_pk_mul_f32 v[42:43], v[36:37], v[36:37] op_sel_hi:[0,1]
	v_mov_b32_e32 v54, v3
	v_add_f32_e32 v2, 1.0, v38
	v_mov_b32_e32 v33, v15
	v_cndmask_b32_e64 v8, 1.0, v49, s[10:11]
	v_mov_b32_e32 v14, v45
	v_mov_b32_e32 v15, v47
	v_mov_b32_e32 v45, v46
	v_pk_mul_f32 v[46:47], v[198:199], v[54:55]
	v_mov_b32_e32 v42, v0
	v_add_f32_e32 v1, 1.0, v56
	v_rcp_f32_e32 v2, v2
	v_mul_f32_e32 v55, v8, v47
	v_pk_mul_f32 v[32:33], v[32:33], v[42:43]
	v_rcp_f32_e32 v1, v1
	v_mul_f32_e32 v54, v41, v55
	v_mov_b32_e32 v41, v33
	s_nop 1
	v_permlane32_swap_b32_e32 v33, v41
	v_mov_b32_e32 v39, v48
	v_mov_b32_e32 v48, v2
	v_mul_f32_e32 v9, v9, v54
	v_pk_mul_f32 v[38:39], v[38:39], v[48:49]
	v_mul_f32_e32 v8, v40, v9
	v_mul_f32_e32 v40, v56, v1
	v_pk_mul_f32 v[48:49], v[38:39], v[46:47]
	s_waitcnt lgkmcnt(0)
	v_pk_mul_f32 v[32:33], v[32:33], v[40:41]
	v_cndmask_b32_e64 v34, 1.0, v41, s[10:11]
	v_pk_mul_f32 v[32:33], v[32:33], v[48:49]
	v_mov_b32_e32 v39, v32
	s_nop 1
	v_permlane32_swap_b32_e32 v32, v39
	v_cndmask_b32_e64 v10, 1.0, v10, s[10:11]
	v_pk_mul_f32 v[14:15], v[14:15], v[54:55]
	v_pk_mul_f32 v[8:9], v[44:45], v[8:9]
	v_cvt_pk_bf16_f32 v225, v14, v15
	s_waitcnt lgkmcnt(0)
	v_mul_f32_e32 v32, v32, v39
	v_mul_f32_e32 v197, v32, v33
	v_cndmask_b32_e64 v32, 1.0, v39, s[10:11]
	v_mul_f32_e32 v33, v32, v33
	v_mul_f32_e32 v32, v46, v33
	v_pk_mul_f32 v[2:3], v[2:3], v[32:33]
	v_mul_f32_e32 v33, v34, v49
	v_mul_f32_e32 v39, v38, v32
	v_mul_f32_e32 v32, v37, v33
	v_mul_f32_e32 v37, v36, v32
	v_mul_f32_e32 v36, v35, v37
	v_mul_f32_e32 v35, v199, v10
	v_mul_f32_e32 v38, v40, v39
	v_mul_f32_e32 v34, v13, v35
	v_pk_mul_f32 v[0:1], v[0:1], v[38:39]
	v_pk_mul_f32 v[4:5], v[4:5], v[36:37]
	v_pk_mul_f32 v[6:7], v[6:7], v[32:33]
	v_mov_b32_e32 v32, v51
	v_mov_b32_e32 v33, v53
	v_mul_f32_e32 v11, v11, v34
	v_pk_mul_f32 v[32:33], v[32:33], v[34:35]
	v_mov_b32_e32 v51, v52
	v_mul_f32_e32 v10, v12, v11
	v_cvt_pk_bf16_f32 v214, v0, v1
	v_cvt_pk_bf16_f32 v215, v2, v3
	v_cvt_pk_bf16_f32 v216, v4, v5
	v_cvt_pk_bf16_f32 v217, v6, v7
	v_pk_mul_f32 v[10:11], v[50:51], v[10:11]
	v_cvt_pk_bf16_f32 v227, v32, v33
	v_mfma_f32_32x32x16_bf16 v[48:63], v[28:31], v[214:217], v[64:79]
	v_cvt_pk_bf16_f32 v224, v8, v9
	v_cvt_pk_bf16_f32 v226, v10, v11
	v_mfma_f32_32x32x16_bf16 v[32:47], v[16:19], v[214:217], v[80:95]
	s_nop 0
	v_mfma_f32_32x32x16_bf16 v[48:63], v[24:27], v[224:227], v[48:63]
	v_mfma_f32_32x32x16_bf16 v[32:47], v[20:23], v[224:227], v[32:47]
	v_mfma_f32_32x32x16_bf16 v[16:31], v[168:171], v[214:217], v[96:111]
	v_mfma_f32_32x32x16_bf16 v[0:15], v[164:167], v[214:217], v[112:127]
	v_mfma_f32_32x32x16_bf16 v[16:31], v[172:175], v[224:227], v[16:31]
	v_mfma_f32_32x32x16_bf16 v[0:15], v[160:163], v[224:227], v[0:15]
